# hy_s3: long-conv output (YT) loads issued together with the conv taps instead of after their wait
# baseline (speedup 1.0000x reference)
; __device__ __forceinline__ float bf2f(bf16_t b) { return __uint_as_float(((unsigned)b) << 16); }
; #define p (*kparams())
; __device__ __forceinline__ void conv3_16(const bf16_t* P, const float* cw, const float* cbias, int b, int t0, int col, float (&out)[16]) {
;     const int cc = col - 1024; const float w0 = cw[cc], w1 = cw[1536 + cc], w2 = cw[3072 + cc], bb = cbias[cc];
;     float xv[18];
; #pragma unroll
;     for (int q = 0; q < 18; ++q) { const int t = t0 - 1 + q; xv[q] = (t >= 0 && t < T) ? bf2f(P[(size_t)row_of(b, t) * NMIX + col]) : 0.f; }
; #pragma unroll
;     for (int tt = 0; tt < 16; ++tt) out[tt] = bb + w0 * xv[tt] + w1 * xv[tt + 1] + w2 * xv[tt + 2];
; }
; __device__ __forceinline__ void hy_s3_item(CParams& p, int layer, int item) {
;     ...
;     const bf16_t* P = (const bf16_t*)(p.ws + R_PMIX);
;     const float* cw = p.in[12] + layer * 3 * 1536; const float* cbias = p.in[13] + layer * 1536;
;     float x0[16];
;     conv3_16(P, cw, cbias, b, t0, 1024 + ch, x0);
;     const bf16_t* YT = (const bf16_t*)(p.ws + R_YT) + ((size_t)ch * 2 + b) * TF + (t0 + FOFF);
;     const u32x4 ya = *(const u32x4*)YT, yb = *(const u32x4*)(YT + 8);
.LBB0_919:
	s_or_b64 exec, exec, s[14:15]
	v_lshlrev_b32_e32 v150, 1, v1
	v_add_u32_e32 v151, s11, v150
	v_mov_b64_e32 v[152:153], s[30:31]
	s_movk_i32 s14, 0x4100
	v_mad_i64_i32 v[152:153], s[14:15], v151, s14, v[152:153]
	v_mov_b32_e32 v154, v0
	v_mov_b32_e32 v155, v2
	v_lshl_add_u64 v[154:155], v[154:155], 1, v[152:153]
	s_mov_b64 s[14:15], 0x3a270000
	v_lshl_add_u64 v[154:155], v[154:155], 0, s[14:15]
	global_load_dwordx4 v[140:143], v[154:155], off
	global_load_dwordx4 v[144:147], v[154:155], off offset:16
	s_waitcnt vmcnt(0)
	v_lshlrev_b32_e32 v10, 16, v120
	v_lshlrev_b32_e32 v9, 16, v121
	v_lshlrev_b32_e32 v14, 16, v122
	v_lshlrev_b32_e32 v13, 16, v123
	v_lshlrev_b32_e32 v16, 16, v124
	v_lshlrev_b32_e32 v15, 16, v125
	v_lshlrev_b32_e32 v18, 16, v126
	v_lshlrev_b32_e32 v17, 16, v127
	v_lshlrev_b32_e32 v20, 16, v128
	v_lshlrev_b32_e32 v19, 16, v129
	v_lshlrev_b32_e32 v29, 16, v130
	v_lshlrev_b32_e32 v28, 16, v131
	v_lshlrev_b32_e32 v31, 16, v132
	v_lshlrev_b32_e32 v30, 16, v133
	v_lshlrev_b32_e32 v33, 16, v134
	v_lshlrev_b32_e32 v32, 16, v135
	v_lshlrev_b32_e32 v35, 16, v136
	v_lshlrev_b32_e32 v34, 16, v137
	s_waitcnt vmcnt(0)
	v_fma_f32 v22, v6, v18, v3
	v_fmac_f32_e32 v22, v7, v17
	v_fma_f32 v21, v6, v17, v3
	v_fma_f32 v24, v6, v16, v3
	v_fmac_f32_e32 v22, v8, v20
	v_fmac_f32_e32 v21, v7, v20
	v_fma_f32 v20, v6, v20, v3
	v_fmac_f32_e32 v24, v7, v15
	v_fma_f32 v23, v6, v15, v3
	v_fmac_f32_e32 v21, v8, v19
	v_fmac_f32_e32 v20, v7, v19
	v_fma_f32 v19, v6, v19, v3
	v_fmac_f32_e32 v24, v8, v18
	v_fmac_f32_e32 v23, v7, v18
	v_fmac_f32_e32 v19, v7, v29
	v_fma_f32 v18, v6, v29, v3
	v_fmac_f32_e32 v23, v8, v17
	v_fmac_f32_e32 v19, v8, v28
	v_fmac_f32_e32 v18, v7, v28
	v_fma_f32 v17, v6, v28, v3
	v_lshlrev_b32_e32 v28, 1, v1
	v_add_u32_e32 v1, s11, v28
	v_mov_b64_e32 v[4:5], s[30:31]
	s_movk_i32 s14, 0x4100
	v_mad_i64_i32 v[4:5], s[14:15], v1, s14, v[4:5]
	v_mov_b32_e32 v1, v2
	v_fma_f32 v36, v6, v10, v3
	v_fma_f32 v26, v6, v14, v3
	v_fma_f32 v25, v6, v13, v3
	v_lshl_add_u64 v[0:1], v[0:1], 1, v[4:5]
	s_mov_b64 s[14:15], 0x3a270000
	v_fmac_f32_e32 v36, v7, v9
	v_fma_f32 v27, v6, v9, v3
	v_fmac_f32_e32 v26, v7, v13
	v_fmac_f32_e32 v25, v7, v16
	v_lshl_add_u64 v[4:5], v[0:1], 0, s[14:15]
	s_mov_b32 s14, 0x3a270000
	v_fmac_f32_e32 v36, v8, v14
	v_fmac_f32_e32 v27, v7, v14
	v_fmac_f32_e32 v26, v8, v16
	v_fmac_f32_e32 v25, v8, v15
	v_fma_f32 v16, v6, v31, v3
	v_fma_f32 v15, v6, v30, v3
	v_fma_f32 v14, v6, v33, v3
	v_fmac_f32_e32 v3, v6, v32
	v_add_co_u32_e32 v0, vcc, s14, v0
	v_fmac_f32_e32 v17, v7, v31
	v_fmac_f32_e32 v16, v7, v30
	v_fmac_f32_e32 v15, v7, v33
	v_fmac_f32_e32 v14, v7, v32
	v_fmac_f32_e32 v3, v7, v35
	v_addc_co_u32_e32 v1, vcc, 0, v1, vcc
	v_fmac_f32_e32 v27, v8, v13
	v_fmac_f32_e32 v20, v8, v29
	v_fmac_f32_e32 v18, v8, v31
	v_fmac_f32_e32 v17, v8, v30
	v_fmac_f32_e32 v16, v8, v33
	v_fmac_f32_e32 v15, v8, v32
	v_fmac_f32_e32 v14, v8, v35
	v_fmac_f32_e32 v3, v8, v34
	v_mov_b32_e32 v8, v140
	v_mov_b32_e32 v9, v141
	v_mov_b32_e32 v10, v142
	v_mov_b32_e32 v11, v143
	s_nop 0
	v_mov_b32_e32 v4, v144
	v_mov_b32_e32 v5, v145
	v_mov_b32_e32 v6, v146
	v_mov_b32_e32 v7, v147
	s_add_i32 s14, s44, s39
	s_addk_i32 s45, 0x4000
	s_addk_i32 s14, 0xff80
	s_cmp_eq_u32 s36, 0
	s_cselect_b32 s14, s45, s14
	v_add_u32_e32 v0, s14, v12
	v_mov_b32_e32 v29, v2
	v_lshl_add_u64 v[12:13], s[4:5], 0, v[28:29]
	s_waitcnt vmcnt(1)
; __device__ __forceinline__ unsigned f2bf(float f) { return pk2(f, 0.f) & 0xffffu; }
; __device__ __forceinline__ void hy_s3_item(CParams& p, int layer, int item) {
;     ...
; #pragma unroll
;     for (int tt = 0; tt < 16; ++tt) { const unsigned wv = (tt < 8) ? ya[tt >> 1] : yb[(tt - 8) >> 1];
;         const float y = (tt & 1) ? __uint_as_float(wv & 0xffff0000u) : __uint_as_float(wv << 16);
;         Z[(size_t)row_bci(b, c, 16 * tq + tt) * D + 512 + ch] = (bf16_t)f2bf(x0[tt] * y); }
	v_lshlrev_b32_e32 v1, 16, v8
	v_mul_f32_e32 v1, v36, v1
	v_cvt_pk_bf16_f32 v30, v1, s0
	v_ashrrev_i32_e32 v1, 31, v0
	v_lshlrev_b64 v[28:29], 12, v[0:1]
	v_lshl_add_u64 v[28:29], v[12:13], 0, v[28:29]
	global_store_short v[28:29], v30, off offset:1024
	v_or_b32_e32 v28, 1, v0
	v_and_b32_e32 v1, 0xffff0000, v8
	v_ashrrev_i32_e32 v29, 31, v28
	v_mul_f32_e32 v1, v27, v1
	v_lshlrev_b64 v[28:29], 12, v[28:29]
	v_cvt_pk_bf16_f32 v1, v1, s0
	v_lshl_add_u64 v[28:29], v[12:13], 0, v[28:29]
	global_store_short v[28:29], v1, off offset:1024
	v_lshlrev_b32_e32 v1, 16, v9
	v_mul_f32_e32 v1, v26, v1
	v_or_b32_e32 v26, 2, v0
	v_ashrrev_i32_e32 v27, 31, v26
	v_lshlrev_b64 v[26:27], 12, v[26:27]
	v_cvt_pk_bf16_f32 v1, v1, s0
	v_lshl_add_u64 v[26:27], v[12:13], 0, v[26:27]
	v_or_b32_e32 v8, 3, v0
	global_store_short v[26:27], v1, off offset:1024
	v_and_b32_e32 v1, 0xffff0000, v9
	v_ashrrev_i32_e32 v9, 31, v8
	v_mul_f32_e32 v1, v25, v1
	v_lshlrev_b64 v[8:9], 12, v[8:9]
	v_cvt_pk_bf16_f32 v1, v1, s0
	v_lshl_add_u64 v[8:9], v[12:13], 0, v[8:9]
	global_store_short v[8:9], v1, off offset:1024
	v_or_b32_e32 v8, 4, v0
	v_lshlrev_b32_e32 v1, 16, v10
	v_ashrrev_i32_e32 v9, 31, v8
	v_mul_f32_e32 v1, v24, v1
	v_lshlrev_b64 v[8:9], 12, v[8:9]
	v_cvt_pk_bf16_f32 v1, v1, s0
	v_lshl_add_u64 v[8:9], v[12:13], 0, v[8:9]
	global_store_short v[8:9], v1, off offset:1024
	v_or_b32_e32 v8, 5, v0
	v_and_b32_e32 v1, 0xffff0000, v10
	v_ashrrev_i32_e32 v9, 31, v8
	v_mul_f32_e32 v1, v23, v1
	v_lshlrev_b64 v[8:9], 12, v[8:9]
	v_cvt_pk_bf16_f32 v1, v1, s0
	v_lshl_add_u64 v[8:9], v[12:13], 0, v[8:9]
	global_store_short v[8:9], v1, off offset:1024
	v_or_b32_e32 v8, 6, v0
	v_lshlrev_b32_e32 v1, 16, v11
	v_ashrrev_i32_e32 v9, 31, v8
	v_mul_f32_e32 v1, v22, v1
	v_lshlrev_b64 v[8:9], 12, v[8:9]
	v_cvt_pk_bf16_f32 v1, v1, s0
	v_lshl_add_u64 v[8:9], v[12:13], 0, v[8:9]
	global_store_short v[8:9], v1, off offset:1024
	v_or_b32_e32 v8, 7, v0
	v_and_b32_e32 v1, 0xffff0000, v11
	v_ashrrev_i32_e32 v9, 31, v8
	v_mul_f32_e32 v1, v21, v1
	v_lshlrev_b64 v[8:9], 12, v[8:9]
	v_cvt_pk_bf16_f32 v1, v1, s0
	v_lshl_add_u64 v[8:9], v[12:13], 0, v[8:9]
	global_store_short v[8:9], v1, off offset:1024
	v_or_b32_e32 v8, 8, v0
	s_waitcnt vmcnt(8)
	v_lshlrev_b32_e32 v1, 16, v4
	v_ashrrev_i32_e32 v9, 31, v8
	v_mul_f32_e32 v1, v20, v1
	v_lshlrev_b64 v[8:9], 12, v[8:9]
	v_cvt_pk_bf16_f32 v1, v1, s0
	v_lshl_add_u64 v[8:9], v[12:13], 0, v[8:9]
	global_store_short v[8:9], v1, off offset:1024
	v_or_b32_e32 v8, 9, v0
	v_and_b32_e32 v1, 0xffff0000, v4
	v_ashrrev_i32_e32 v9, 31, v8
	v_mul_f32_e32 v1, v19, v1
	v_lshlrev_b64 v[8:9], 12, v[8:9]
	v_cvt_pk_bf16_f32 v1, v1, s0
	v_lshl_add_u64 v[8:9], v[12:13], 0, v[8:9]
	global_store_short v[8:9], v1, off offset:1024
	v_or_b32_e32 v8, 10, v0
	v_lshlrev_b32_e32 v1, 16, v5
	v_ashrrev_i32_e32 v9, 31, v8
	v_mul_f32_e32 v1, v18, v1
	v_lshlrev_b64 v[8:9], 12, v[8:9]
	v_cvt_pk_bf16_f32 v1, v1, s0
	v_lshl_add_u64 v[8:9], v[12:13], 0, v[8:9]
	v_or_b32_e32 v4, 11, v0
	global_store_short v[8:9], v1, off offset:1024
	v_and_b32_e32 v1, 0xffff0000, v5
	v_ashrrev_i32_e32 v5, 31, v4
	v_mul_f32_e32 v1, v17, v1
	v_lshlrev_b64 v[4:5], 12, v[4:5]
	v_cvt_pk_bf16_f32 v1, v1, s0
	v_lshl_add_u64 v[4:5], v[12:13], 0, v[4:5]
	global_store_short v[4:5], v1, off offset:1024
	v_or_b32_e32 v4, 12, v0
	v_lshlrev_b32_e32 v1, 16, v6
	v_ashrrev_i32_e32 v5, 31, v4
	v_mul_f32_e32 v1, v16, v1
	v_lshlrev_b64 v[4:5], 12, v[4:5]
	v_cvt_pk_bf16_f32 v1, v1, s0
	v_lshl_add_u64 v[4:5], v[12:13], 0, v[4:5]
	global_store_short v[4:5], v1, off offset:1024
	v_or_b32_e32 v4, 13, v0
	v_and_b32_e32 v1, 0xffff0000, v6
	v_ashrrev_i32_e32 v5, 31, v4
	v_mul_f32_e32 v1, v15, v1
	v_lshlrev_b64 v[4:5], 12, v[4:5]
	v_cvt_pk_bf16_f32 v1, v1, s0
	v_lshl_add_u64 v[4:5], v[12:13], 0, v[4:5]
	global_store_short v[4:5], v1, off offset:1024
	v_or_b32_e32 v4, 14, v0
	v_lshlrev_b32_e32 v1, 16, v7
	v_ashrrev_i32_e32 v5, 31, v4
	v_mul_f32_e32 v1, v14, v1
	v_lshlrev_b64 v[4:5], 12, v[4:5]
	v_cvt_pk_bf16_f32 v1, v1, s0
	v_lshl_add_u64 v[4:5], v[12:13], 0, v[4:5]
	global_store_short v[4:5], v1, off offset:1024
	v_and_b32_e32 v1, 0xffff0000, v7
	v_mul_f32_e32 v1, v3, v1
	v_or_b32_e32 v0, 15, v0
	v_cvt_pk_bf16_f32 v3, v1, s0
	v_ashrrev_i32_e32 v1, 31, v0
	v_lshlrev_b64 v[0:1], 12, v[0:1]
	v_lshl_add_u64 v[0:1], v[12:13], 0, v[0:1]
	global_store_short v[0:1], v3, off offset:1024
